# fused P8 final norm now taken only when the launch-time topology check passed (column groups inside one XCD); otherwise the original two-pass path
# speedup vs baseline: 1.0027x; 1.0027x over previous
.LBB0_938:
	v_mov_b32_e32 v0, 0x20088
	ds_read_b32 v0, v0
	s_waitcnt lgkmcnt(0)
	v_readfirstlane_b32 s98, v0
	s_cmp_eq_u32 s98, 1
	s_cselect_b32 s98, 1, 0
	s_cmpk_eq_i32 s82, 0x100
	s_cselect_b32 s98, s98, 0
	s_cmp_lt_i32 s90, 9
	s_cselect_b64 s[0:1], -1, 0
	s_cmp_gt_i32 s91, 8
	s_cselect_b64 s[2:3], -1, 0
	s_and_b64 s[0:1], s[0:1], s[2:3]
	s_andn2_b64 vcc, exec, s[0:1]
	s_cbranch_vccnz .LBB0_1055
	s_abs_i32 s1, s82
	v_cvt_f32_u32_e32 v0, s1
	s_sub_i32 s2, 0, s1
	s_ashr_i32 s0, s82, 31
	s_mov_b32 s6, 0
	v_rcp_iflag_f32_e32 v0, v0
	s_nop 0
	v_mul_f32_e32 v0, 0x4f7ffffe, v0
	v_cvt_u32_f32_e32 v0, v0
	s_nop 0
	v_readfirstlane_b32 s3, v0
	s_mul_i32 s2, s2, s3
	s_mul_hi_u32 s2, s3, s2
	s_add_i32 s3, s3, s2
	s_lshr_b32 s2, s3, 22
	s_mul_i32 s3, s2, s1
	s_sub_i32 s3, 0x400, s3
	s_add_i32 s4, s2, 1
	s_sub_i32 s5, s3, s1
	s_cmp_ge_u32 s3, s1
	s_cselect_b32 s2, s4, s2
	s_cselect_b32 s3, s5, s3
	s_add_i32 s4, s2, 1
	s_cmp_ge_u32 s3, s1
	s_cselect_b32 s1, s4, s2
	s_xor_b32 s1, s1, s0
	s_sub_i32 s1, s1, s0
	s_mul_i32 s2, s1, s82
	s_cmpk_eq_i32 s2, 0x400
	s_cselect_b32 s57, s1, 0
	s_cmp_lt_i32 s57, 0
	v_readfirstlane_b32 s2, v196
	s_cbranch_scc1 .LBB0_943
	v_sub_u32_e64 v0, s57, 1 clamp
	s_ashr_i32 s4, s94, 31
	v_readfirstlane_b32 s1, v0
	s_mul_i32 s0, s1, s0
	s_mul_hi_u32 s3, s1, s82
	s_add_i32 s3, s3, s0
	s_mul_i32 s1, s1, s82
	s_add_u32 s0, s1, s94
	s_addc_u32 s1, s3, s4
	v_mov_b64_e32 v[0:1], 0x3ff
	v_cmp_gt_i64_e32 vcc, s[0:1], v[0:1]
	v_readlane_b32 s72, v249, 29
	v_readlane_b32 s73, v249, 30
	s_cbranch_vccnz .LBB0_944
	s_ashr_i32 s1, s0, 31
	s_lshr_b32 s1, s1, 29
	s_add_i32 s5, s0, s1
	s_and_b32 s1, s5, -8
	s_sub_i32 s3, s0, s1
	s_cmp_gt_i32 s3, -1
	s_cbranch_scc0 .LBB0_945
	s_lshl_b32 s4, s3, 7
	s_ashr_i32 s0, s5, 3
	s_cbranch_execz .LBB0_946
	s_branch .LBB0_947

.LBB0_991:
	s_cmp_eq_u32 s98, 1
	s_cbranch_scc1 .Lfz_epi
	s_lshl_b32 s8, s22, 8
	v_add_u32_e32 v180, s8, v165
	v_lshl_or_b32 v160, s58, 8, v169
	v_readlane_b32 s4, v249, 44
	v_readlane_b32 s5, v249, 45
	s_ashr_i32 s0, s22, 3
	s_mul_hi_i32 s1, s0, 0x6000
	s_mulk_i32 s0, 0x6000
	s_add_u32 s0, s64, s0
	s_addc_u32 s1, s65, s1
	v_mov_b32_e32 v161, 0
	v_lshl_add_u32 v158, v180, 10, v160
	v_mov_b32_e32 v159, 0
	v_lshl_add_u64 v[156:157], v[160:161], 2, s[0:1]
	v_lshl_add_u64 v[162:163], v[158:159], 1, s[4:5]
	v_lshlrev_b32_e32 v181, 1, v158
	global_load_dwordx4 v[132:135], v[156:157], off
	global_load_dwordx4 v[128:131], v[156:157], off offset:16
	s_mov_b32 s10, 0x8000
	s_mov_b32 s11, 0
	s_mov_b32 s12, 0x28000
	s_mov_b32 s13, 0
	s_mov_b32 s14, 0x8000
	s_mov_b32 s15, 0x10000
	s_mov_b32 s23, 0x18000
	s_mov_b32 s24, 0x40000
	s_mov_b32 s32, 0x48000
	s_mov_b32 s55, 0x50000
	s_mov_b32 s74, 0x58000
	v_mov_b64_e32 v[192:193], v[162:163]
	global_load_dwordx4 v[200:203], v[192:193], off nt
	v_lshl_add_u64 v[192:193], v[192:193], 0, s[10:11]
	global_load_dwordx4 v[204:207], v[192:193], off nt
	global_load_dwordx4 v[184:187], v[156:157], off offset:512
	global_load_dwordx4 v[188:191], v[156:157], off offset:528
	v_lshl_add_u64 v[192:193], v[192:193], 0, s[10:11]
	global_load_dwordx4 v[208:211], v[192:193], off nt
	v_lshl_add_u64 v[192:193], v[192:193], 0, s[10:11]
	global_load_dwordx4 v[212:215], v[192:193], off nt
	v_lshl_add_u64 v[192:193], v[192:193], 0, s[12:13]
	global_load_dwordx4 v[216:219], v[192:193], off nt
	v_lshl_add_u64 v[192:193], v[192:193], 0, s[10:11]
	global_load_dwordx4 v[220:223], v[192:193], off nt
	s_waitcnt vmcnt(7)
	v_lshlrev_b32_e32 v224, 16, v200
	v_and_b32_e32 v225, 0xffff0000, v200
	v_lshlrev_b32_e32 v226, 16, v201
	v_and_b32_e32 v227, 0xffff0000, v201
	v_lshlrev_b32_e32 v228, 16, v202
	v_and_b32_e32 v229, 0xffff0000, v202
	v_lshlrev_b32_e32 v230, 16, v203
	v_and_b32_e32 v231, 0xffff0000, v203
	v_pk_fma_f32 v[124:125], v[124:125], v[132:133], v[224:225]
	v_pk_fma_f32 v[126:127], v[126:127], v[134:135], v[226:227]
	v_pk_fma_f32 v[120:121], v[120:121], v[128:129], v[228:229]
	v_pk_fma_f32 v[122:123], v[122:123], v[130:131], v[230:231]
	v_cvt_pk_bf16_f32 v200, v124, v125
	v_cvt_pk_bf16_f32 v201, v126, v127
	v_cvt_pk_bf16_f32 v202, v120, v121
	v_cvt_pk_bf16_f32 v203, v122, v123
	buffer_store_dwordx4 v[200:203], v181, s[16:19], 0 offen sc1
	s_nop 0
	v_lshl_add_u64 v[192:193], v[192:193], 0, s[10:11]
	global_load_dwordx4 v[200:203], v[192:193], off nt
	s_waitcnt vmcnt(8)
	v_lshlrev_b32_e32 v224, 16, v204
	v_and_b32_e32 v225, 0xffff0000, v204
	v_lshlrev_b32_e32 v226, 16, v205
	v_and_b32_e32 v227, 0xffff0000, v205
	v_lshlrev_b32_e32 v228, 16, v206
	v_and_b32_e32 v229, 0xffff0000, v206
	v_lshlrev_b32_e32 v230, 16, v207
	v_and_b32_e32 v231, 0xffff0000, v207
	v_pk_fma_f32 v[116:117], v[116:117], v[132:133], v[224:225]
	v_pk_fma_f32 v[118:119], v[118:119], v[134:135], v[226:227]
	v_pk_fma_f32 v[112:113], v[112:113], v[128:129], v[228:229]
	v_pk_fma_f32 v[114:115], v[114:115], v[130:131], v[230:231]
	v_cvt_pk_bf16_f32 v204, v116, v117
	v_cvt_pk_bf16_f32 v205, v118, v119
	v_cvt_pk_bf16_f32 v206, v112, v113
	v_cvt_pk_bf16_f32 v207, v114, v115
	buffer_store_dwordx4 v[204:207], v181, s[16:19], s14 offen sc1
	s_nop 0
	v_lshl_add_u64 v[192:193], v[192:193], 0, s[10:11]
	global_load_dwordx4 v[204:207], v[192:193], off nt
	s_waitcnt vmcnt(7)
	v_lshlrev_b32_e32 v224, 16, v208
	v_and_b32_e32 v225, 0xffff0000, v208
	v_lshlrev_b32_e32 v226, 16, v209
	v_and_b32_e32 v227, 0xffff0000, v209
	v_lshlrev_b32_e32 v228, 16, v210
	v_and_b32_e32 v229, 0xffff0000, v210
	v_lshlrev_b32_e32 v230, 16, v211
	v_and_b32_e32 v231, 0xffff0000, v211
	v_pk_fma_f32 v[108:109], v[108:109], v[132:133], v[224:225]
	v_pk_fma_f32 v[110:111], v[110:111], v[134:135], v[226:227]
	v_pk_fma_f32 v[104:105], v[104:105], v[128:129], v[228:229]
	v_pk_fma_f32 v[106:107], v[106:107], v[130:131], v[230:231]
	v_cvt_pk_bf16_f32 v208, v108, v109
	v_cvt_pk_bf16_f32 v209, v110, v111
	v_cvt_pk_bf16_f32 v210, v104, v105
	v_cvt_pk_bf16_f32 v211, v106, v107
	buffer_store_dwordx4 v[208:211], v181, s[16:19], s15 offen sc1
	s_nop 0
	v_mov_b64_e32 v[192:193], v[162:163]
	global_load_dwordx4 v[208:211], v[192:193], off offset:256 nt
	s_waitcnt vmcnt(8)
	v_lshlrev_b32_e32 v224, 16, v212
	v_and_b32_e32 v225, 0xffff0000, v212
	v_lshlrev_b32_e32 v226, 16, v213
	v_and_b32_e32 v227, 0xffff0000, v213
	v_lshlrev_b32_e32 v228, 16, v214
	v_and_b32_e32 v229, 0xffff0000, v214
	v_lshlrev_b32_e32 v230, 16, v215
	v_and_b32_e32 v231, 0xffff0000, v215
	v_pk_fma_f32 v[100:101], v[100:101], v[132:133], v[224:225]
	v_pk_fma_f32 v[102:103], v[102:103], v[134:135], v[226:227]
	v_pk_fma_f32 v[96:97], v[96:97], v[128:129], v[228:229]
	v_pk_fma_f32 v[98:99], v[98:99], v[130:131], v[230:231]
	v_cvt_pk_bf16_f32 v212, v100, v101
	v_cvt_pk_bf16_f32 v213, v102, v103
	v_cvt_pk_bf16_f32 v214, v96, v97
	v_cvt_pk_bf16_f32 v215, v98, v99
	buffer_store_dwordx4 v[212:215], v181, s[16:19], s23 offen sc1
	s_nop 0
	v_lshl_add_u64 v[192:193], v[192:193], 0, s[10:11]
	global_load_dwordx4 v[212:215], v[192:193], off offset:256 nt
	s_waitcnt vmcnt(9)
	v_lshlrev_b32_e32 v224, 16, v216
	v_and_b32_e32 v225, 0xffff0000, v216
	v_lshlrev_b32_e32 v226, 16, v217
	v_and_b32_e32 v227, 0xffff0000, v217
	v_lshlrev_b32_e32 v228, 16, v218
	v_and_b32_e32 v229, 0xffff0000, v218
	v_lshlrev_b32_e32 v230, 16, v219
	v_and_b32_e32 v231, 0xffff0000, v219
	v_pk_fma_f32 v[92:93], v[92:93], v[132:133], v[224:225]
	v_pk_fma_f32 v[94:95], v[94:95], v[134:135], v[226:227]
	v_pk_fma_f32 v[88:89], v[88:89], v[128:129], v[228:229]
	v_pk_fma_f32 v[90:91], v[90:91], v[130:131], v[230:231]
	v_cvt_pk_bf16_f32 v216, v92, v93
	v_cvt_pk_bf16_f32 v217, v94, v95
	v_cvt_pk_bf16_f32 v218, v88, v89
	v_cvt_pk_bf16_f32 v219, v90, v91
	buffer_store_dwordx4 v[216:219], v181, s[16:19], s24 offen sc1
	s_nop 0
	v_lshl_add_u64 v[192:193], v[192:193], 0, s[10:11]
	global_load_dwordx4 v[216:219], v[192:193], off offset:256 nt
	s_waitcnt vmcnt(10)
	v_lshlrev_b32_e32 v224, 16, v220
	v_and_b32_e32 v225, 0xffff0000, v220
	v_lshlrev_b32_e32 v226, 16, v221
	v_and_b32_e32 v227, 0xffff0000, v221
	v_lshlrev_b32_e32 v228, 16, v222
	v_and_b32_e32 v229, 0xffff0000, v222
	v_lshlrev_b32_e32 v230, 16, v223
	v_and_b32_e32 v231, 0xffff0000, v223
	v_pk_fma_f32 v[84:85], v[84:85], v[132:133], v[224:225]
	v_pk_fma_f32 v[86:87], v[86:87], v[134:135], v[226:227]
	v_pk_fma_f32 v[80:81], v[80:81], v[128:129], v[228:229]
	v_pk_fma_f32 v[82:83], v[82:83], v[130:131], v[230:231]
	v_cvt_pk_bf16_f32 v220, v84, v85
	v_cvt_pk_bf16_f32 v221, v86, v87
	v_cvt_pk_bf16_f32 v222, v80, v81
	v_cvt_pk_bf16_f32 v223, v82, v83
	buffer_store_dwordx4 v[220:223], v181, s[16:19], s32 offen sc1
	s_nop 0
	v_lshl_add_u64 v[192:193], v[192:193], 0, s[10:11]
	global_load_dwordx4 v[220:223], v[192:193], off offset:256 nt
	s_waitcnt vmcnt(10)
	v_lshlrev_b32_e32 v224, 16, v200
	v_and_b32_e32 v225, 0xffff0000, v200
	v_lshlrev_b32_e32 v226, 16, v201
	v_and_b32_e32 v227, 0xffff0000, v201
	v_lshlrev_b32_e32 v228, 16, v202
	v_and_b32_e32 v229, 0xffff0000, v202
	v_lshlrev_b32_e32 v230, 16, v203
	v_and_b32_e32 v231, 0xffff0000, v203
	v_pk_fma_f32 v[76:77], v[76:77], v[132:133], v[224:225]
	v_pk_fma_f32 v[78:79], v[78:79], v[134:135], v[226:227]
	v_pk_fma_f32 v[72:73], v[72:73], v[128:129], v[228:229]
	v_pk_fma_f32 v[74:75], v[74:75], v[130:131], v[230:231]
	v_cvt_pk_bf16_f32 v200, v76, v77
	v_cvt_pk_bf16_f32 v201, v78, v79
	v_cvt_pk_bf16_f32 v202, v72, v73
	v_cvt_pk_bf16_f32 v203, v74, v75
	buffer_store_dwordx4 v[200:203], v181, s[16:19], s55 offen sc1
	s_nop 0
	v_lshl_add_u64 v[192:193], v[192:193], 0, s[12:13]
	global_load_dwordx4 v[200:203], v[192:193], off offset:256 nt
	s_waitcnt vmcnt(10)
	v_lshlrev_b32_e32 v224, 16, v204
	v_and_b32_e32 v225, 0xffff0000, v204
	v_lshlrev_b32_e32 v226, 16, v205
	v_and_b32_e32 v227, 0xffff0000, v205
	v_lshlrev_b32_e32 v228, 16, v206
	v_and_b32_e32 v229, 0xffff0000, v206
	v_lshlrev_b32_e32 v230, 16, v207
	v_and_b32_e32 v231, 0xffff0000, v207
	v_pk_fma_f32 v[68:69], v[68:69], v[132:133], v[224:225]
	v_pk_fma_f32 v[70:71], v[70:71], v[134:135], v[226:227]
	v_pk_fma_f32 v[64:65], v[64:65], v[128:129], v[228:229]
	v_pk_fma_f32 v[66:67], v[66:67], v[130:131], v[230:231]
	v_cvt_pk_bf16_f32 v204, v68, v69
	v_cvt_pk_bf16_f32 v205, v70, v71
	v_cvt_pk_bf16_f32 v206, v64, v65
	v_cvt_pk_bf16_f32 v207, v66, v67
	buffer_store_dwordx4 v[204:207], v181, s[16:19], s74 offen sc1
	s_nop 0
	v_lshl_add_u64 v[192:193], v[192:193], 0, s[10:11]
	global_load_dwordx4 v[204:207], v[192:193], off offset:256 nt
	s_waitcnt vmcnt(10)
	v_lshlrev_b32_e32 v224, 16, v208
	v_and_b32_e32 v225, 0xffff0000, v208
	v_lshlrev_b32_e32 v226, 16, v209
	v_and_b32_e32 v227, 0xffff0000, v209
	v_lshlrev_b32_e32 v228, 16, v210
	v_and_b32_e32 v229, 0xffff0000, v210
	v_lshlrev_b32_e32 v230, 16, v211
	v_and_b32_e32 v231, 0xffff0000, v211
	v_pk_fma_f32 v[60:61], v[60:61], v[184:185], v[224:225]
	v_pk_fma_f32 v[62:63], v[62:63], v[186:187], v[226:227]
	v_pk_fma_f32 v[56:57], v[56:57], v[188:189], v[228:229]
	v_pk_fma_f32 v[58:59], v[58:59], v[190:191], v[230:231]
	v_cvt_pk_bf16_f32 v208, v60, v61
	v_cvt_pk_bf16_f32 v209, v62, v63
	v_cvt_pk_bf16_f32 v210, v56, v57
	v_cvt_pk_bf16_f32 v211, v58, v59
	buffer_store_dwordx4 v[208:211], v181, s[16:19], 0 offen offset:256 sc1
	s_nop 0
	v_lshl_add_u64 v[192:193], v[192:193], 0, s[10:11]
	global_load_dwordx4 v[208:211], v[192:193], off offset:256 nt
	s_waitcnt vmcnt(10)
	v_lshlrev_b32_e32 v224, 16, v212
	v_and_b32_e32 v225, 0xffff0000, v212
	v_lshlrev_b32_e32 v226, 16, v213
	v_and_b32_e32 v227, 0xffff0000, v213
	v_lshlrev_b32_e32 v228, 16, v214
	v_and_b32_e32 v229, 0xffff0000, v214
	v_lshlrev_b32_e32 v230, 16, v215
	v_and_b32_e32 v231, 0xffff0000, v215
	v_pk_fma_f32 v[52:53], v[52:53], v[184:185], v[224:225]
	v_pk_fma_f32 v[54:55], v[54:55], v[186:187], v[226:227]
	v_pk_fma_f32 v[48:49], v[48:49], v[188:189], v[228:229]
	v_pk_fma_f32 v[50:51], v[50:51], v[190:191], v[230:231]
	v_cvt_pk_bf16_f32 v212, v52, v53
	v_cvt_pk_bf16_f32 v213, v54, v55
	v_cvt_pk_bf16_f32 v214, v48, v49
	v_cvt_pk_bf16_f32 v215, v50, v51
	buffer_store_dwordx4 v[212:215], v181, s[16:19], s14 offen offset:256 sc1
	s_nop 0
	v_lshl_add_u64 v[192:193], v[192:193], 0, s[10:11]
	global_load_dwordx4 v[212:215], v[192:193], off offset:256 nt
	s_waitcnt vmcnt(10)
	v_lshlrev_b32_e32 v224, 16, v216
	v_and_b32_e32 v225, 0xffff0000, v216
	v_lshlrev_b32_e32 v226, 16, v217
	v_and_b32_e32 v227, 0xffff0000, v217
	v_lshlrev_b32_e32 v228, 16, v218
	v_and_b32_e32 v229, 0xffff0000, v218
	v_lshlrev_b32_e32 v230, 16, v219
	v_and_b32_e32 v231, 0xffff0000, v219
	v_pk_fma_f32 v[44:45], v[44:45], v[184:185], v[224:225]
	v_pk_fma_f32 v[46:47], v[46:47], v[186:187], v[226:227]
	v_pk_fma_f32 v[40:41], v[40:41], v[188:189], v[228:229]
	v_pk_fma_f32 v[42:43], v[42:43], v[190:191], v[230:231]
	v_cvt_pk_bf16_f32 v216, v44, v45
	v_cvt_pk_bf16_f32 v217, v46, v47
	v_cvt_pk_bf16_f32 v218, v40, v41
	v_cvt_pk_bf16_f32 v219, v42, v43
	buffer_store_dwordx4 v[216:219], v181, s[16:19], s15 offen offset:256 sc1
	s_waitcnt vmcnt(9)
	v_lshlrev_b32_e32 v224, 16, v220
	v_and_b32_e32 v225, 0xffff0000, v220
	v_lshlrev_b32_e32 v226, 16, v221
	v_and_b32_e32 v227, 0xffff0000, v221
	v_lshlrev_b32_e32 v228, 16, v222
	v_and_b32_e32 v229, 0xffff0000, v222
	v_lshlrev_b32_e32 v230, 16, v223
	v_and_b32_e32 v231, 0xffff0000, v223
	v_pk_fma_f32 v[36:37], v[36:37], v[184:185], v[224:225]
	v_pk_fma_f32 v[38:39], v[38:39], v[186:187], v[226:227]
	v_pk_fma_f32 v[32:33], v[32:33], v[188:189], v[228:229]
	v_pk_fma_f32 v[34:35], v[34:35], v[190:191], v[230:231]
	v_cvt_pk_bf16_f32 v220, v36, v37
	v_cvt_pk_bf16_f32 v221, v38, v39
	v_cvt_pk_bf16_f32 v222, v32, v33
	v_cvt_pk_bf16_f32 v223, v34, v35
	buffer_store_dwordx4 v[220:223], v181, s[16:19], s23 offen offset:256 sc1
	s_waitcnt vmcnt(8)
	v_lshlrev_b32_e32 v224, 16, v200
	v_and_b32_e32 v225, 0xffff0000, v200
	v_lshlrev_b32_e32 v226, 16, v201
	v_and_b32_e32 v227, 0xffff0000, v201
	v_lshlrev_b32_e32 v228, 16, v202
	v_and_b32_e32 v229, 0xffff0000, v202
	v_lshlrev_b32_e32 v230, 16, v203
	v_and_b32_e32 v231, 0xffff0000, v203
	v_pk_fma_f32 v[28:29], v[28:29], v[184:185], v[224:225]
	v_pk_fma_f32 v[30:31], v[30:31], v[186:187], v[226:227]
	v_pk_fma_f32 v[24:25], v[24:25], v[188:189], v[228:229]
	v_pk_fma_f32 v[26:27], v[26:27], v[190:191], v[230:231]
	v_cvt_pk_bf16_f32 v200, v28, v29
	v_cvt_pk_bf16_f32 v201, v30, v31
	v_cvt_pk_bf16_f32 v202, v24, v25
	v_cvt_pk_bf16_f32 v203, v26, v27
	buffer_store_dwordx4 v[200:203], v181, s[16:19], s24 offen offset:256 sc1
	s_waitcnt vmcnt(7)
	v_lshlrev_b32_e32 v224, 16, v204
	v_and_b32_e32 v225, 0xffff0000, v204
	v_lshlrev_b32_e32 v226, 16, v205
	v_and_b32_e32 v227, 0xffff0000, v205
	v_lshlrev_b32_e32 v228, 16, v206
	v_and_b32_e32 v229, 0xffff0000, v206
	v_lshlrev_b32_e32 v230, 16, v207
	v_and_b32_e32 v231, 0xffff0000, v207
	v_pk_fma_f32 v[20:21], v[20:21], v[184:185], v[224:225]
	v_pk_fma_f32 v[22:23], v[22:23], v[186:187], v[226:227]
	v_pk_fma_f32 v[16:17], v[16:17], v[188:189], v[228:229]
	v_pk_fma_f32 v[18:19], v[18:19], v[190:191], v[230:231]
	v_cvt_pk_bf16_f32 v204, v20, v21
	v_cvt_pk_bf16_f32 v205, v22, v23
	v_cvt_pk_bf16_f32 v206, v16, v17
	v_cvt_pk_bf16_f32 v207, v18, v19
	buffer_store_dwordx4 v[204:207], v181, s[16:19], s32 offen offset:256 sc1
	s_waitcnt vmcnt(6)
	v_lshlrev_b32_e32 v224, 16, v208
	v_and_b32_e32 v225, 0xffff0000, v208
	v_lshlrev_b32_e32 v226, 16, v209
	v_and_b32_e32 v227, 0xffff0000, v209
	v_lshlrev_b32_e32 v228, 16, v210
	v_and_b32_e32 v229, 0xffff0000, v210
	v_lshlrev_b32_e32 v230, 16, v211
	v_and_b32_e32 v231, 0xffff0000, v211
	v_pk_fma_f32 v[12:13], v[12:13], v[184:185], v[224:225]
	v_pk_fma_f32 v[14:15], v[14:15], v[186:187], v[226:227]
	v_pk_fma_f32 v[8:9], v[8:9], v[188:189], v[228:229]
	v_pk_fma_f32 v[10:11], v[10:11], v[190:191], v[230:231]
	v_cvt_pk_bf16_f32 v208, v12, v13
	v_cvt_pk_bf16_f32 v209, v14, v15
	v_cvt_pk_bf16_f32 v210, v8, v9
	v_cvt_pk_bf16_f32 v211, v10, v11
	buffer_store_dwordx4 v[208:211], v181, s[16:19], s55 offen offset:256 sc1
	s_waitcnt vmcnt(5)
	v_lshlrev_b32_e32 v224, 16, v212
	v_and_b32_e32 v225, 0xffff0000, v212
	v_lshlrev_b32_e32 v226, 16, v213
	v_and_b32_e32 v227, 0xffff0000, v213
	v_lshlrev_b32_e32 v228, 16, v214
	v_and_b32_e32 v229, 0xffff0000, v214
	v_lshlrev_b32_e32 v230, 16, v215
	v_and_b32_e32 v231, 0xffff0000, v215
	v_pk_fma_f32 v[4:5], v[4:5], v[184:185], v[224:225]
	v_pk_fma_f32 v[6:7], v[6:7], v[186:187], v[226:227]
	v_pk_fma_f32 v[0:1], v[0:1], v[188:189], v[228:229]
	v_pk_fma_f32 v[2:3], v[2:3], v[190:191], v[230:231]
	v_cvt_pk_bf16_f32 v212, v4, v5
	v_cvt_pk_bf16_f32 v213, v6, v7
	v_cvt_pk_bf16_f32 v214, v0, v1
	v_cvt_pk_bf16_f32 v215, v2, v3
	buffer_store_dwordx4 v[212:215], v181, s[16:19], s74 offen offset:256 sc1
	s_mov_b64 s[0:1], -1
	s_and_b64 vcc, exec, s[38:39]
	s_cbranch_vccz .LBB0_1002
	s_waitcnt vmcnt(0)
	s_barrier
	s_and_saveexec_b64 s[0:1], s[92:93]
	s_cbranch_execz .LBB0_998
	s_mov_b64 s[6:7], exec
	v_mbcnt_lo_u32_b32 v0, s6, 0
	v_mbcnt_hi_u32_b32 v0, s7, v0
	v_cmp_eq_u32_e32 vcc, 0, v0
	s_and_saveexec_b64 s[4:5], vcc
	s_cbranch_execz .LBB0_995
	s_ashr_i32 s23, s22, 31
	s_lshl_b64 s[10:11], s[22:23], 2
	s_add_u32 s10, s33, s10
	s_addc_u32 s11, s56, s11
	s_bcnt1_i32_b64 s6, s[6:7]
	v_mov_b32_e32 v1, s6
	global_atomic_add v1, v139, v1, s[10:11] sc0

.LBB0_1010:
	s_andn2_b64 vcc, exec, s[0:1]
	s_cbranch_vccz .LBB0_1012
	s_mov_b32 s24, s22
	s_cmp_eq_u32 s98, 1
	s_cselect_b32 s24, -1, s24
	s_mov_b32 s8, s58
	s_mov_b32 s58, s80
	s_mov_b32 s22, s81
	s_mov_b64 s[4:5], s[52:53]
	s_mov_b64 s[0:1], s[50:51]
	s_mov_b32 s2, s79
	s_branch .LBB0_952

.LBB0_1012:
	s_waitcnt vmcnt(0)
	s_lshl_b32 s6, s78, 6
	s_lshl_b32 s18, s58, 6
	s_mov_b32 s14, s22
	s_cmp_eq_u32 s98, 1
	s_cselect_b32 s14, -1, s14
	s_barrier

	.amdhsa_kernel _Z10fwd_kernel4Args
		.amdhsa_group_segment_fixed_size 0
		.amdhsa_private_segment_fixed_size 0
		.amdhsa_kernarg_size 448
		.amdhsa_user_sgpr_count 2
		.amdhsa_user_sgpr_dispatch_ptr 0
		.amdhsa_user_sgpr_queue_ptr 0
		.amdhsa_user_sgpr_kernarg_segment_ptr 1
		.amdhsa_user_sgpr_dispatch_id 0
		.amdhsa_user_sgpr_kernarg_preload_length 0
		.amdhsa_user_sgpr_kernarg_preload_offset 0
		.amdhsa_user_sgpr_private_segment_size 0
		.amdhsa_uses_dynamic_stack 0
		.amdhsa_enable_private_segment 0
		.amdhsa_system_sgpr_workgroup_id_x 1
		.amdhsa_system_sgpr_workgroup_id_y 0
		.amdhsa_system_sgpr_workgroup_id_z 0
		.amdhsa_system_sgpr_workgroup_info 0
		.amdhsa_system_vgpr_workitem_id 2
		.amdhsa_next_free_vgpr 250
		.amdhsa_next_free_sgpr 100
		.amdhsa_accum_offset 252
		.amdhsa_reserve_vcc 1
		.amdhsa_float_round_mode_32 0
		.amdhsa_float_round_mode_16_64 0
		.amdhsa_float_denorm_mode_32 3
		.amdhsa_float_denorm_mode_16_64 3
		.amdhsa_dx10_clamp 1
		.amdhsa_ieee_mode 1
		.amdhsa_fp16_overflow 0
		.amdhsa_tg_split 0
		.amdhsa_exception_fp_ieee_invalid_op 0
		.amdhsa_exception_fp_denorm_src 0
		.amdhsa_exception_fp_ieee_div_zero 0
		.amdhsa_exception_fp_ieee_overflow 0
		.amdhsa_exception_fp_ieee_underflow 0
		.amdhsa_exception_fp_ieee_inexact 0
		.amdhsa_exception_int_div_zero 0
	.end_amdhsa_kernel

amdhsa.kernels:
  - .agpr_count:     0
    .args:
      - .offset:         0
        .size:           192
        .value_kind:     by_value
      - .offset:         192
        .size:           4
        .value_kind:     hidden_block_count_x
      - .offset:         196
        .size:           4
        .value_kind:     hidden_block_count_y
      - .offset:         200
        .size:           4
        .value_kind:     hidden_block_count_z
      - .offset:         204
        .size:           2
        .value_kind:     hidden_group_size_x
      - .offset:         206
        .size:           2
        .value_kind:     hidden_group_size_y
      - .offset:         208
        .size:           2
        .value_kind:     hidden_group_size_z
      - .offset:         210
        .size:           2
        .value_kind:     hidden_remainder_x
      - .offset:         212
        .size:           2
        .value_kind:     hidden_remainder_y
      - .offset:         214
        .size:           2
        .value_kind:     hidden_remainder_z
      - .offset:         232
        .size:           8
        .value_kind:     hidden_global_offset_x
      - .offset:         240
        .size:           8
        .value_kind:     hidden_global_offset_y
      - .offset:         248
        .size:           8
        .value_kind:     hidden_global_offset_z
      - .offset:         256
        .size:           2
        .value_kind:     hidden_grid_dims
      - .offset:         280
        .size:           8
        .value_kind:     hidden_multigrid_sync_arg
      - .offset:         312
        .size:           4
        .value_kind:     hidden_dynamic_lds_size
    .group_segment_fixed_size: 0
    .kernarg_segment_align: 8
    .kernarg_segment_size: 448
    .language:       OpenCL C
    .language_version:
      - 2
      - 0
    .max_flat_workgroup_size: 512
    .name:           _Z10fwd_kernel4Args
    .private_segment_fixed_size: 0
    .sgpr_count:     106
    .sgpr_spill_count: 93
    .symbol:         _Z10fwd_kernel4Args.kd
    .uniform_work_group_size: 1
    .uses_dynamic_stack: false
    .vgpr_count:     250
    .vgpr_spill_count: 0
    .wavefront_size: 64
